# layer-1 pa/pb/o conversion moved from the L1 up1 slot to the L0 up2 slot
# speedup vs baseline: 1.0049x; 1.0049x over previous
; __device__ __forceinline__ void prologue(const kptr_t kp, LAS float* scr, int gw, int NGW, int lane) {
;     ...
;     for (int it = gw; it < IT_TOTAL; it += NGW) {
;         int r = it;
.LBB0_1270:
	s_cmp_lt_u32 s2, 44
	s_cbranch_scc1 .Lslot_4_skip
	v_writelane_b32 v250, s3, 0
	v_writelane_b32 v250, s4, 1
	v_writelane_b32 v250, s5, 2
	v_writelane_b32 v250, s6, 3
	v_writelane_b32 v250, s7, 4
	v_writelane_b32 v250, s8, 5
	v_writelane_b32 v250, s9, 6
	v_writelane_b32 v250, s10, 7
	v_writelane_b32 v250, s11, 8
	v_writelane_b32 v250, s12, 9
	v_writelane_b32 v250, s13, 10
	v_writelane_b32 v250, s14, 11
	v_writelane_b32 v250, s15, 12
	v_writelane_b32 v250, s16, 13
	v_writelane_b32 v250, s17, 14
	v_writelane_b32 v250, s18, 15
	v_writelane_b32 v250, s19, 16
	v_writelane_b32 v250, s20, 17
	v_writelane_b32 v250, s21, 18
	v_writelane_b32 v250, s22, 19
	v_writelane_b32 v250, s23, 20
	v_writelane_b32 v250, s24, 21
	v_writelane_b32 v250, s25, 22
	v_writelane_b32 v250, s26, 23
	v_writelane_b32 v250, s27, 24
	v_writelane_b32 v250, s28, 25
	v_writelane_b32 v250, s29, 26
	v_writelane_b32 v250, s30, 27
	v_writelane_b32 v250, s31, 28
	v_writelane_b32 v250, s32, 29
	v_writelane_b32 v250, s33, 30
	v_writelane_b32 v250, s34, 31
	v_writelane_b32 v250, s35, 32
	v_writelane_b32 v250, s36, 33
	v_writelane_b32 v250, s37, 34
	v_writelane_b32 v250, s38, 35
	v_writelane_b32 v250, s39, 36
	v_writelane_b32 v250, s40, 37
	v_writelane_b32 v250, s41, 38
	v_writelane_b32 v250, s42, 39
	v_writelane_b32 v250, s43, 40
	v_writelane_b32 v250, s44, 41
	v_writelane_b32 v250, s45, 42
	v_writelane_b32 v250, s46, 43
	v_writelane_b32 v250, s47, 44
	v_writelane_b32 v250, s48, 45
	v_writelane_b32 v250, s49, 46
	v_writelane_b32 v250, s50, 47
	v_writelane_b32 v250, s51, 48
	v_writelane_b32 v250, s52, 49
	v_writelane_b32 v250, s53, 50
	v_writelane_b32 v250, s54, 51
	v_writelane_b32 v250, s55, 52
	v_writelane_b32 v250, s56, 53
	v_writelane_b32 v250, s57, 54
	v_writelane_b32 v250, s58, 55
	v_writelane_b32 v250, s59, 56
	v_writelane_b32 v250, s60, 57
	v_writelane_b32 v250, s61, 58
	v_writelane_b32 v250, s62, 59
	v_writelane_b32 v250, s63, 60
	v_writelane_b32 v250, s64, 61
	v_writelane_b32 v250, s65, 62
	v_writelane_b32 v250, s66, 63
	v_writelane_b32 v251, s67, 0
	v_writelane_b32 v251, s68, 1
	v_writelane_b32 v251, s69, 2
	v_writelane_b32 v251, s70, 3
	v_writelane_b32 v251, s71, 4
	v_writelane_b32 v251, s72, 5
	v_writelane_b32 v251, s73, 6
	v_writelane_b32 v251, s74, 7
	v_writelane_b32 v251, s75, 8
	v_writelane_b32 v251, s76, 9
	v_writelane_b32 v251, s77, 10
	v_writelane_b32 v251, s78, 11
	v_writelane_b32 v251, s79, 12
	v_writelane_b32 v251, s80, 13
	v_writelane_b32 v251, s81, 14
	v_writelane_b32 v251, s82, 15
	v_writelane_b32 v251, s83, 16
	v_writelane_b32 v251, s84, 17
	v_writelane_b32 v251, s85, 18
	v_writelane_b32 v251, s86, 19
	v_writelane_b32 v251, s87, 20
	v_writelane_b32 v251, s88, 21
	v_writelane_b32 v251, s89, 22
	v_writelane_b32 v251, s90, 23
	v_writelane_b32 v251, s91, 24
	v_writelane_b32 v251, s92, 25
	v_writelane_b32 v251, s93, 26
	v_writelane_b32 v251, s94, 27
	v_writelane_b32 v251, s95, 28
	v_writelane_b32 v251, s96, 29
	v_writelane_b32 v251, s97, 30
	v_mov_b32_e32 v236, v200
	v_mov_b32_e32 v237, v201
	v_mov_b32_e32 v238, v202
	v_mov_b32_e32 v239, v203
	v_mov_b32_e32 v240, v204
	v_mov_b32_e32 v241, v205
	v_mov_b32_e32 v242, v206
	v_mov_b32_e32 v243, v207
	v_mov_b32_e32 v244, v208
	v_mov_b32_e32 v245, v209
	v_mov_b32_e32 v246, v210
	v_mov_b32_e32 v247, v211
	s_mov_b32 s98, 0x44a0
	s_mov_b32 s99, 0x6a0
	s_mov_b32 s100, 0x5880
	s_mov_b32 s101, 14
	s_branch .Lcv_hop2

; __device__ __forceinline__ void prologue(const kptr_t kp, LAS float* scr, int gw, int NGW, int lane) {
;     ...
;     for (int it = gw; it < IT_TOTAL; it += NGW) {
;         int r = it;
.LBB0_1490:
	s_cmp_lt_u32 s2, 44
	s_cbranch_scc1 .Lslot_5_skip
	v_writelane_b32 v250, s3, 0
	v_writelane_b32 v250, s4, 1
	v_writelane_b32 v250, s5, 2
	v_writelane_b32 v250, s6, 3
	v_writelane_b32 v250, s7, 4
	v_writelane_b32 v250, s8, 5
	v_writelane_b32 v250, s9, 6
	v_writelane_b32 v250, s10, 7
	v_writelane_b32 v250, s11, 8
	v_writelane_b32 v250, s12, 9
	v_writelane_b32 v250, s13, 10
	v_writelane_b32 v250, s14, 11
	v_writelane_b32 v250, s15, 12
	v_writelane_b32 v250, s16, 13
	v_writelane_b32 v250, s17, 14
	v_writelane_b32 v250, s18, 15
	v_writelane_b32 v250, s19, 16
	v_writelane_b32 v250, s20, 17
	v_writelane_b32 v250, s21, 18
	v_writelane_b32 v250, s22, 19
	v_writelane_b32 v250, s23, 20
	v_writelane_b32 v250, s24, 21
	v_writelane_b32 v250, s25, 22
	v_writelane_b32 v250, s26, 23
	v_writelane_b32 v250, s27, 24
	v_writelane_b32 v250, s28, 25
	v_writelane_b32 v250, s29, 26
	v_writelane_b32 v250, s30, 27
	v_writelane_b32 v250, s31, 28
	v_writelane_b32 v250, s32, 29
	v_writelane_b32 v250, s33, 30
	v_writelane_b32 v250, s34, 31
	v_writelane_b32 v250, s35, 32
	v_writelane_b32 v250, s36, 33
	v_writelane_b32 v250, s37, 34
	v_writelane_b32 v250, s38, 35
	v_writelane_b32 v250, s39, 36
	v_writelane_b32 v250, s40, 37
	v_writelane_b32 v250, s41, 38
	v_writelane_b32 v250, s42, 39
	v_writelane_b32 v250, s43, 40
	v_writelane_b32 v250, s44, 41
	v_writelane_b32 v250, s45, 42
	v_writelane_b32 v250, s46, 43
	v_writelane_b32 v250, s47, 44
	v_writelane_b32 v250, s48, 45
	v_writelane_b32 v250, s49, 46
	v_writelane_b32 v250, s50, 47
	v_writelane_b32 v250, s51, 48
	v_writelane_b32 v250, s52, 49
	v_writelane_b32 v250, s53, 50
	v_writelane_b32 v250, s54, 51
	v_writelane_b32 v250, s55, 52
	v_writelane_b32 v250, s56, 53
	v_writelane_b32 v250, s57, 54
	v_writelane_b32 v250, s58, 55
	v_writelane_b32 v250, s59, 56
	v_writelane_b32 v250, s60, 57
	v_writelane_b32 v250, s61, 58
	v_writelane_b32 v250, s62, 59
	v_writelane_b32 v250, s63, 60
	v_writelane_b32 v250, s64, 61
	v_writelane_b32 v250, s65, 62
	v_writelane_b32 v250, s66, 63
	v_writelane_b32 v251, s67, 0
	v_writelane_b32 v251, s68, 1
	v_writelane_b32 v251, s69, 2
	v_writelane_b32 v251, s70, 3
	v_writelane_b32 v251, s71, 4
	v_writelane_b32 v251, s72, 5
	v_writelane_b32 v251, s73, 6
	v_writelane_b32 v251, s74, 7
	v_writelane_b32 v251, s75, 8
	v_writelane_b32 v251, s76, 9
	v_writelane_b32 v251, s77, 10
	v_writelane_b32 v251, s78, 11
	v_writelane_b32 v251, s79, 12
	v_writelane_b32 v251, s80, 13
	v_writelane_b32 v251, s81, 14
	v_writelane_b32 v251, s82, 15
	v_writelane_b32 v251, s83, 16
	v_writelane_b32 v251, s84, 17
	v_writelane_b32 v251, s85, 18
	v_writelane_b32 v251, s86, 19
	v_writelane_b32 v251, s87, 20
	v_writelane_b32 v251, s88, 21
	v_writelane_b32 v251, s89, 22
	v_writelane_b32 v251, s90, 23
	v_writelane_b32 v251, s91, 24
	v_writelane_b32 v251, s92, 25
	v_writelane_b32 v251, s93, 26
	v_writelane_b32 v251, s94, 27
	v_writelane_b32 v251, s95, 28
	v_writelane_b32 v251, s96, 29
	v_writelane_b32 v251, s97, 30
	v_mov_b32_e32 v236, v200
	v_mov_b32_e32 v237, v201
	v_mov_b32_e32 v238, v202
	v_mov_b32_e32 v239, v203
	v_mov_b32_e32 v240, v204
	v_mov_b32_e32 v241, v205
	v_mov_b32_e32 v242, v206
	v_mov_b32_e32 v243, v207
	v_mov_b32_e32 v244, v208
	v_mov_b32_e32 v245, v209
	v_mov_b32_e32 v246, v210
	v_mov_b32_e32 v247, v211
	s_mov_b32 s98, 0x5720
	s_mov_b32 s99, 0x6a0
	s_mov_b32 s100, 0x7180
	s_mov_b32 s101, 15
	s_branch .Lcv_hop3
